# SWA and dilated units: chunk bits rotated so each XCD owns a contiguous chunk range (K/V tiles fetched by one XCD instead of 4-5)
# baseline (speedup 1.0000x reference)
; template <int MODE>
; DI void flash_loop(char* smem, const bf16_t* Kbase, size_t ldk, const bf16_t* Vtbase, size_t ldv, ull tiles, ull wtiles,
;                    const bf16x8 (&qf)[4], f32x16 (&o)[2], float& m, float& l, int tq, int tqmin, int tqmax, int maxdist, const float* cn_lds, ull lmask) {
;     ...
;   auto issue = [&](int kt, u32x4 (&rk)[2], u32x4 (&rv)[2]) {
; #pragma unroll
;     for (int q = 0; q < 2; ++q) { rk[q] = *(const u32x4*)(Kbase + (size_t)(64 * kt + lr + 32 * q) * ldk + c8); rv[q] = *(const u32x4*)(Vtbase + (size_t)(lr + 32 * q) * ldv + 64 * kt + c8); }
;   };
;   auto stash = [&](int stage, const u32x4 (&rk)[2], const u32x4 (&rv)[2]) {
;     bf16_t* Ks = (bf16_t*)(smem + stage * (2 * 64 * LSTR * 2)); bf16_t* Vs = Ks + 64 * LSTR;
; #pragma unroll
;     for (int q = 0; q < 2; ++q) { *(u32x4*)(Ks + (lr + 32 * q) * LSTR + c8) = rk[q]; *(u32x4*)(Vs + (lr + 32 * q) * LSTR + c8) = rv[q]; }
;   };
;   auto next_tile = [&]() -> int { if (!tiles) return -1; const int t = __builtin_ctzll(tiles); tiles &= tiles - 1; return t; };
;   auto compute = [&](int kt, int stage) {
;     if (!((wtiles >> kt) & 1ull)) return;
;     const bf16_t* Ks = (const bf16_t*)(smem + stage * (2 * 64 * LSTR * 2)); const bf16_t* Vs = Ks + 64 * LSTR;
;     const bool sel = ((lmask >> kt) & 1ull) != 0;
;     const bool interior = (64 * kt + 63 <= tqmin) && (MODE != 0 || (tqmax - 64 * kt <= maxdist));
;     int hm = 3;
; DI void dil_unit(const Params& p, int gi, int dlog, int u, char* smem, bool probe = false) {
;   const int tid = otid(), lane = tid & 63, w = __builtin_amdgcn_readfirstlane(tid >> 6), r = lane & 31, h = lane >> 5;
;   const int L = SEQ >> dlog, nch = L >> 5;
;   const int chunk = u % nch, kvh = (u / nch) & 3, bq = u / (nch * 4);
;   const int q0 = chunk * 32, head = kvh * 4 + w, tq = q0 + r; const size_t row = (size_t)bq * L + tq;
;   __syncthreads();
;   bf16_t* Qg = p.Q + (size_t)gi * NTOK * 1024;
;   bf16x8 qf[4]; load_q(Qg + row * 1024 + head * 64, qf);
;   f32x16 o[2]; zero_o(o);
;   float m = -1e30f, l = 0.f;
;   int lo = (q0 - 128) >> 6; lo = lo < 0 ? 0 : lo; const int hi = (q0 + 31) >> 6;
;   const ull tiles = tile_range(lo, hi);
;   flash_loop<0>(smem, p.Kb + (size_t)gi * NTOK * 256 + (size_t)bq * L * 256 + kvh * 64, 256, p.Vt + (size_t)gi * NTOK * 256 + (size_t)(bq * 4 + kvh) * 64 * L, L, tiles, tiles, qf, o, m, l, tq, q0, q0 + 31, 128, nullptr, 0ull);
.LBB0_914:
	s_ashr_i32 s2, s1, 12
	v_mov_b32_e32 v156, v167
	s_lshl_b32 s3, s2, 1
	s_and_b32 s4, s1, 0xfff
	v_readfirstlane_b32 s5, v156
	s_ashr_i32 s7, s5, 6
	s_lshr_b32 s5, 0x80, s3
	s_add_i32 s5, s5, -1
	s_and_b32 s29, s5, s4
	s_and_b32 s100, s29, 7
	s_lshr_b32 s29, s29, 3
	s_sub_i32 s101, 4, s3
	s_lshl_b32 s100, s100, s101
	s_or_b32 s29, s29, s100
	s_lshr_b32 s100, s4, 9
	s_add_i32 s29, s29, s100
	s_and_b32 s29, s29, s5
	s_sub_i32 s5, 7, s3
	s_lshr_b32 s5, s4, s5
	s_lshr_b32 s10, 0x1000, s3
	s_and_b32 s6, s5, 3
	s_sub_i32 s3, 9, s3
	s_lshr_b32 s11, s4, s3
	s_lshl_b32 s3, s6, 2
	s_lshl_b32 s5, s29, 5
	s_add_i32 s4, s7, s3
	s_ashr_i32 s3, s2, 31
	v_readlane_b32 s12, v229, 29
	v_and_or_b32 v157, v156, 31, s5
	s_mul_i32 s58, s11, s10
	s_lshl_b64 s[8:9], s[2:3], 26
	v_readlane_b32 s24, v229, 41
	v_add_u32_e32 v146, s58, v157
	v_mov_b32_e32 v147, v1
	v_readlane_b32 s25, v229, 42
	s_add_u32 s8, s24, s8
	s_addc_u32 s9, s25, s9
	v_lshlrev_b64 v[2:3], 11, v[146:147]
	v_lshl_add_u64 v[2:3], s[8:9], 0, v[2:3]
	s_lshl_b32 s8, s4, 6
	s_ashr_i32 s9, s8, 31
	v_lshl_add_u64 v[148:149], s[8:9], 1, v[2:3]
	s_lshr_b32 s8, s29, 1
	s_add_i32 s28, s5, 0xffffff80
	s_add_i32 s8, s8, 1
	s_ashr_i32 s7, s28, 6
	s_lshl_b64 s[8:9], -1, s8
	s_max_i32 s7, s7, 0
	s_not_b64 s[8:9], s[8:9]
	s_cmpk_lt_u32 s29, 0x7e
	s_cselect_b32 s9, s9, -1
	s_cselect_b32 s8, s8, -1
	s_lshl_b64 s[30:31], -1, s7
	s_and_b64 s[8:9], s[30:31], s[8:9]
	v_readlane_b32 s26, v229, 43
	v_readlane_b32 s27, v229, 44
	s_cmp_eq_u64 s[8:9], 0
	s_barrier
	v_readlane_b32 s13, v229, 30
	v_readlane_b32 s14, v229, 31
	v_readlane_b32 s15, v229, 32
	v_readlane_b32 s16, v229, 33
	v_readlane_b32 s17, v229, 34
	v_readlane_b32 s18, v229, 35
	v_readlane_b32 s19, v229, 36
	v_readlane_b32 s20, v229, 37
	v_readlane_b32 s21, v229, 38
	v_readlane_b32 s22, v229, 39
	v_readlane_b32 s23, v229, 40
	s_cbranch_scc1 .LBB0_917
	s_lshl_b64 s[30:31], s[2:3], 24
	s_add_u32 s7, s26, s30
	s_addc_u32 s29, s27, s31
	s_lshl_b64 s[36:37], s[58:59], 9
	s_add_u32 s7, s7, s36
	s_addc_u32 s29, s29, s37
	s_lshl_b32 s33, s6, 6
	s_lshl_b32 s6, s6, 7
	s_add_u32 s6, s7, s6
	s_addc_u32 s7, s29, 0
	v_readlane_b32 s12, v230, 51
	v_readlane_b32 s13, v230, 52
	s_add_u32 s29, s12, s30
	s_addc_u32 s36, s13, s31
	s_lshl_b32 s11, s11, 8
	s_or_b32 s11, s33, s11
	s_mul_i32 s58, s11, s10
	s_lshl_b64 s[30:31], s[58:59], 1
	s_add_u32 s30, s29, s30
	s_addc_u32 s31, s36, s31
	s_add_u32 s36, s8, -1
	s_ff1_i32_b64 s33, s[8:9]
	v_lshlrev_b32_e32 v0, 1, v166
	s_addc_u32 s37, s9, -1
	s_lshl_b32 s11, s33, 6
	v_lshl_add_u64 v[2:3], v[148:149], 0, v[0:1]
	v_add_lshl_u32 v0, s11, v169, 9
	global_load_dwordx4 v[98:101], v[2:3], off
	global_load_dwordx4 v[102:105], v[2:3], off offset:32
	global_load_dwordx4 v[106:109], v[2:3], off offset:64
	global_load_dwordx4 v[110:113], v[2:3], off offset:96
	v_lshl_add_u64 v[2:3], s[6:7], 0, v[0:1]
	v_lshlrev_b32_e32 v0, 1, v168
	v_lshl_add_u64 v[2:3], v[2:3], 0, v[0:1]
	global_load_dwordx4 v[114:117], v[2:3], off
	v_mul_u32_u24_e32 v2, s10, v169
	v_lshlrev_b32_e32 v2, 1, v2
	v_mov_b32_e32 v3, v1
	v_lshl_add_u64 v[2:3], s[30:31], 0, v[2:3]
	s_lshl_b32 s58, s33, 7
	v_lshl_add_u64 v[4:5], v[2:3], 0, s[58:59]
	v_lshl_add_u64 v[4:5], v[4:5], 0, v[0:1]
	global_load_dwordx4 v[118:121], v[4:5], off
	v_add_lshl_u32 v4, s11, v171, 9
	v_mov_b32_e32 v5, v1
	v_lshl_add_u64 v[4:5], s[6:7], 0, v[4:5]
	v_lshl_add_u64 v[4:5], v[4:5], 0, v[0:1]
	s_lshl_b32 s10, s10, 6
	s_mov_b32 s11, s59
	global_load_dwordx4 v[122:125], v[4:5], off
	v_lshl_add_u64 v[4:5], v[2:3], 0, s[10:11]
	v_lshl_add_u64 v[6:7], v[4:5], 0, s[58:59]
	v_lshl_add_u64 v[6:7], v[6:7], 0, v[0:1]
	global_load_dwordx4 v[126:129], v[6:7], off
	s_and_b64 s[10:11], s[36:37], s[8:9]
	s_ff1_i32_b64 s29, s[10:11]
	s_cmp_lg_u64 s[10:11], 0
	s_cselect_b32 s67, s29, -1
	s_cmp_lt_i32 s67, 0
	v_readlane_b32 s14, v230, 53
	v_readlane_b32 s15, v230, 54
	v_readlane_b32 s16, v230, 55
	v_readlane_b32 s17, v230, 56
	v_readlane_b32 s18, v230, 57
	v_readlane_b32 s19, v230, 58
	v_readlane_b32 s20, v230, 59
	v_readlane_b32 s21, v230, 60
	v_readlane_b32 s22, v230, 61
	v_readlane_b32 s23, v230, 62
	v_readlane_b32 s24, v230, 63
	v_readlane_b32 s25, v229, 0
	v_readlane_b32 s26, v229, 1
	v_readlane_b32 s27, v229, 2
	s_cbranch_scc1 .LBB0_918
	s_lshl_b32 s29, s67, 6
	v_add_u32_e32 v6, s29, v169
	v_mov_b32_e32 v7, v1
	v_lshlrev_b64 v[6:7], 9, v[6:7]
	v_lshl_add_u64 v[6:7], s[6:7], 0, v[6:7]
	v_lshl_add_u64 v[6:7], v[6:7], 0, v[0:1]
	s_lshl_b32 s58, s67, 7
	global_load_dwordx4 v[130:133], v[6:7], off
	v_lshl_add_u64 v[6:7], v[2:3], 0, s[58:59]
	v_lshl_add_u64 v[6:7], v[6:7], 0, v[0:1]
	global_load_dwordx4 v[134:137], v[6:7], off
	v_add_u32_e32 v6, s29, v171
	v_mov_b32_e32 v7, v1
	v_lshlrev_b64 v[6:7], 9, v[6:7]
	v_lshl_add_u64 v[6:7], s[6:7], 0, v[6:7]
	v_lshl_add_u64 v[6:7], v[6:7], 0, v[0:1]
	global_load_dwordx4 v[138:141], v[6:7], off
	v_lshl_add_u64 v[6:7], v[4:5], 0, s[58:59]
	v_lshl_add_u64 v[6:7], v[6:7], 0, v[0:1]
	global_load_dwordx4 v[142:145], v[6:7], off
	s_branch .LBB0_919

; template <int MODE>
; DI void flash_loop(char* smem, const bf16_t* Kbase, size_t ldk, const bf16_t* Vtbase, size_t ldv, ull tiles, ull wtiles,
;                    const bf16x8 (&qf)[4], f32x16 (&o)[2], float& m, float& l, int tq, int tqmin, int tqmax, int maxdist, const float* cn_lds, ull lmask) {
;     ...
;   auto issue = [&](int kt, u32x4 (&rk)[2], u32x4 (&rv)[2]) {
; #pragma unroll
;     for (int q = 0; q < 2; ++q) { rk[q] = *(const u32x4*)(Kbase + (size_t)(64 * kt + lr + 32 * q) * ldk + c8); rv[q] = *(const u32x4*)(Vtbase + (size_t)(lr + 32 * q) * ldv + 64 * kt + c8); }
;   };
;   auto stash = [&](int stage, const u32x4 (&rk)[2], const u32x4 (&rv)[2]) {
;     bf16_t* Ks = (bf16_t*)(smem + stage * (2 * 64 * LSTR * 2)); bf16_t* Vs = Ks + 64 * LSTR;
; #pragma unroll
;     for (int q = 0; q < 2; ++q) { *(u32x4*)(Ks + (lr + 32 * q) * LSTR + c8) = rk[q]; *(u32x4*)(Vs + (lr + 32 * q) * LSTR + c8) = rv[q]; }
;   };
;   auto next_tile = [&]() -> int { if (!tiles) return -1; const int t = __builtin_ctzll(tiles); tiles &= tiles - 1; return t; };
;   auto compute = [&](int kt, int stage) {
;     if (!((wtiles >> kt) & 1ull)) return;
;     const bf16_t* Ks = (const bf16_t*)(smem + stage * (2 * 64 * LSTR * 2)); const bf16_t* Vs = Ks + 64 * LSTR;
;     const bool sel = ((lmask >> kt) & 1ull) != 0;
;     const bool interior = (64 * kt + 63 <= tqmin) && (MODE != 0 || (tqmax - 64 * kt <= maxdist));
;     int hm = 3;
;     if (MODE == 0) {
;       hm = 0;
;       if (64 * kt <= tqmax && 64 * kt + 31 >= tqmin - maxdist) hm |= 1;
; DI void swa_unit(const Params& p, int u, char* smem, bool probe = false) {
;   const int tid = otid(), lane = tid & 63, w = __builtin_amdgcn_readfirstlane(tid >> 6), r = lane & 31, h = lane >> 5;
;   const int chunk = u & 127, kvh = (u >> 7) & 3, b = u >> 9;
;   const int q0 = chunk * 32, head = kvh * 4 + w, tq = q0 + r; const size_t tok = (size_t)b * SEQ + tq;
;   __syncthreads();
;   bf16x8 qf[4]; load_q(p.Q + tok * 1024 + head * 64, qf);
;   f32x16 o[2]; zero_o(o);
;   float m = p.sinks[head] * 1.4426950408889634f, l = (h == 0) ? 1.f : 0.f;
;   int lo = (q0 - 127) >> 6; lo = lo < 0 ? 0 : lo; const int hi = (q0 + 31) >> 6;
;   const ull tiles = tile_range(lo, hi);
;   flash_loop<0>(smem, p.Kb + (size_t)b * SEQ * 256 + kvh * 64, 256, p.Vt + (size_t)(b * 4 + kvh) * 64 * SEQ, SEQ, tiles, tiles, qf, o, m, l, tq, q0, q0 + 31, 127, nullptr, 0ull);
.LBB0_982:
	v_mov_b32_e32 v0, v167
	s_bfe_u32 s10, s1, 0x20007
	v_readfirstlane_b32 s2, v0
	s_ashr_i32 s8, s1, 9
	s_and_b32 s100, s1, 7
	s_bfe_u32 s3, s1, 0x40003
	s_lshl_b32 s100, s100, 4
	s_or_b32 s3, s3, s100
	s_lshl_b32 s3, s3, 5
	s_ashr_i32 s2, s2, 6
	s_and_b32 s28, s3, 0xfe0
	s_lshl_b32 s4, s10, 2
	s_ashr_i32 s9, s8, 31
	s_add_i32 s2, s2, s4
	v_and_or_b32 v154, v0, 31, s28
	s_lshl_b64 s[4:5], s[8:9], 12
	s_add_i32 s29, s28, 0xffffff81
	v_or_b32_e32 v146, s4, v154
	s_ashr_i32 s4, s29, 6
	s_bfe_u32 s3, s3, 0x60006
	s_max_i32 s6, s4, 0
	s_add_i32 s4, s3, 1
	v_mov_b32_e32 v147, s5
	s_lshl_b64 s[4:5], -1, s4
	s_not_b64 s[4:5], s[4:5]
	s_cmp_lg_u32 s3, 63
	v_and_b32_e32 v0, 32, v0
	s_cselect_b32 s5, s5, -1
	s_cselect_b32 s4, s4, -1
	s_lshl_b64 s[6:7], -1, s6
	s_and_b64 s[4:5], s[4:5], s[6:7]
	v_cmp_eq_u32_e32 vcc, 0, v0
	s_cmp_eq_u64 s[4:5], 0
	s_nop 0
	v_cndmask_b32_e64 v159, 0, 1.0, vcc
	s_barrier
	s_cbranch_scc1 .LBB0_980
	v_readlane_b32 s12, v229, 29
	v_lshlrev_b64 v[2:3], 11, v[146:147]
	v_readlane_b32 s24, v229, 41
	v_readlane_b32 s25, v229, 42
	s_lshl_b32 s6, s2, 6
	v_readlane_b32 s13, v229, 30
	v_readlane_b32 s14, v229, 31
	v_readlane_b32 s15, v229, 32
	v_lshl_add_u64 v[2:3], s[24:25], 0, v[2:3]
	s_ashr_i32 s7, s6, 31
	s_ashr_i32 s3, s2, 31
	v_lshl_add_u64 v[2:3], s[6:7], 1, v[2:3]
	s_lshl_b64 s[6:7], s[2:3], 2
	v_readlane_b32 s12, v229, 25
	v_lshlrev_b32_e32 v0, 1, v166
	v_readlane_b32 s13, v229, 26
	s_add_u32 s6, s12, s6
	v_lshl_add_u64 v[2:3], v[2:3], 0, v[0:1]
	s_addc_u32 s7, s13, s7
	v_readlane_b32 s26, v229, 43
	global_load_dwordx4 v[98:101], v[2:3], off
	global_load_dwordx4 v[102:105], v[2:3], off offset:32
	global_load_dwordx4 v[106:109], v[2:3], off offset:64
	global_load_dwordx4 v[110:113], v[2:3], off offset:96
	global_load_dword v6, v1, s[6:7]
	s_lshl_b64 s[6:7], s[8:9], 21
	v_readlane_b32 s27, v229, 44
	s_add_u32 s3, s26, s6
	s_addc_u32 s7, s27, s7
	s_lshl_b32 s6, s10, 7
	s_add_u32 s6, s3, s6
	s_addc_u32 s7, s7, 0
	s_lshl_b32 s3, s8, 2
	s_or_b32 s8, s3, s10
	v_readlane_b32 s16, v229, 33
	v_readlane_b32 s17, v229, 34
	v_readlane_b32 s18, v229, 35
	v_readlane_b32 s19, v229, 36
	v_readlane_b32 s20, v229, 37
	v_readlane_b32 s21, v229, 38
	v_readlane_b32 s22, v229, 39
	v_readlane_b32 s23, v229, 40
	v_readlane_b32 s14, v229, 27
	v_readlane_b32 s15, v229, 28
	s_ashr_i32 s9, s8, 31
	s_lshl_b64 s[8:9], s[8:9], 19
	v_readlane_b32 s12, v230, 51
	v_readlane_b32 s13, v230, 52
	s_add_u32 s8, s12, s8
	s_addc_u32 s9, s13, s9
	s_add_u32 s10, s4, -1
	s_ff1_i32_b64 s33, s[4:5]
	s_addc_u32 s11, s5, -1
	s_lshl_b32 s3, s33, 6
	v_add_lshl_u32 v0, s3, v169, 9
	v_lshl_add_u64 v[2:3], s[6:7], 0, v[0:1]
	v_lshlrev_b32_e32 v0, 1, v168
	v_lshl_add_u64 v[2:3], v[2:3], 0, v[0:1]
	global_load_dwordx4 v[114:117], v[2:3], off
	v_lshlrev_b32_e32 v2, 1, v170
	v_mov_b32_e32 v3, v1
	v_lshl_add_u64 v[2:3], s[8:9], 0, v[2:3]
	s_lshl_b32 s58, s33, 7
	v_lshl_add_u64 v[4:5], v[2:3], 0, s[58:59]
	v_lshl_add_u64 v[4:5], v[4:5], 0, v[0:1]
	global_load_dwordx4 v[118:121], v[4:5], off
	v_add_lshl_u32 v4, s3, v171, 9
	v_mov_b32_e32 v5, v1
	v_lshl_add_u64 v[4:5], s[6:7], 0, v[4:5]
	v_lshl_add_u64 v[4:5], v[4:5], 0, v[0:1]
	global_load_dwordx4 v[122:125], v[4:5], off
	v_lshlrev_b32_e32 v4, 1, v176
	v_mov_b32_e32 v5, v1
	v_lshl_add_u64 v[4:5], s[8:9], 0, v[4:5]
	v_lshl_add_u64 v[8:9], v[4:5], 0, s[58:59]
	v_lshl_add_u64 v[8:9], v[8:9], 0, v[0:1]
	global_load_dwordx4 v[126:129], v[8:9], off
	s_and_b64 s[8:9], s[10:11], s[4:5]
	s_ff1_i32_b64 s3, s[8:9]
	s_cmp_lg_u64 s[8:9], 0
	s_cselect_b32 s64, s3, -1
	s_cmp_lt_i32 s64, 0
	v_readlane_b32 s14, v230, 53
	v_readlane_b32 s15, v230, 54
	v_readlane_b32 s16, v230, 55
	v_readlane_b32 s17, v230, 56
	v_readlane_b32 s18, v230, 57
	v_readlane_b32 s19, v230, 58
	v_readlane_b32 s20, v230, 59
	v_readlane_b32 s21, v230, 60
	v_readlane_b32 s22, v230, 61
	v_readlane_b32 s23, v230, 62
	v_readlane_b32 s24, v230, 63
	v_readlane_b32 s25, v229, 0
	v_readlane_b32 s26, v229, 1
	v_readlane_b32 s27, v229, 2
	s_cbranch_scc1 .LBB0_985
	s_lshl_b32 s3, s64, 6
	v_add_u32_e32 v8, s3, v169
	v_mov_b32_e32 v9, v1
	v_lshlrev_b64 v[8:9], 9, v[8:9]
	v_lshl_add_u64 v[8:9], s[6:7], 0, v[8:9]
	v_lshl_add_u64 v[8:9], v[8:9], 0, v[0:1]
	s_lshl_b32 s58, s64, 7
	global_load_dwordx4 v[130:133], v[8:9], off
	v_lshl_add_u64 v[8:9], v[2:3], 0, s[58:59]
	v_lshl_add_u64 v[8:9], v[8:9], 0, v[0:1]
	global_load_dwordx4 v[134:137], v[8:9], off
	v_add_u32_e32 v8, s3, v171
	v_mov_b32_e32 v9, v1
	v_lshlrev_b64 v[8:9], 9, v[8:9]
	v_lshl_add_u64 v[8:9], s[6:7], 0, v[8:9]
	v_lshl_add_u64 v[8:9], v[8:9], 0, v[0:1]
	global_load_dwordx4 v[138:141], v[8:9], off
	v_lshl_add_u64 v[8:9], v[4:5], 0, s[58:59]
	v_lshl_add_u64 v[8:9], v[8:9], 0, v[0:1]
	global_load_dwordx4 v[142:145], v[8:9], off
	s_branch .LBB0_986
